# v059 with coarser LDS waits in the static-stabiliser attention loop (one lgkmcnt wait per two MFMAs, one vmcnt wait per tile write)
# baseline (speedup 1.0000x reference)
.Lattn_fx_top:
	s_add_i32 s11, s10, -1
	s_min_i32 s1, s11, s58
	s_mul_i32 s44, s1, 0xa0000
	s_add_u32 s44, s3, s44
	s_addc_u32 s45, s12, 0
	s_lshl_b32 s46, s1, 7
	s_add_u32 s46, s15, s46
	s_addc_u32 s47, s23, 0
	s_add_i32 s24, s10, -2
	s_cmp_lt_u32 s24, s16
	s_cselect_b64 s[0:1], -1, 0
	s_waitcnt lgkmcnt(0)
	s_barrier
	ds_read_b128 v[162:165], v193
	ds_read_b128 v[178:181], v193 offset:4608
	ds_read_b128 v[166:169], v193 offset:32
	ds_read_b128 v[182:185], v193 offset:4640
	ds_read_b128 v[170:173], v193 offset:64
	ds_read_b128 v[186:189], v193 offset:4672
	ds_read_b128 v[174:177], v193 offset:96
	ds_read_b128 v[82:85], v193 offset:4704
	global_load_dwordx4 v[154:157], v252, s[44:45] offset:1024
	global_load_dwordx4 v[158:161], v253, s[46:47]
	v_exp_f32_e32 v66, v66
	v_exp_f32_e32 v67, v67
	v_exp_f32_e32 v68, v68
	v_exp_f32_e32 v69, v69
	v_add_f32_e32 v246, v66, v67
	v_cvt_pk_bf16_f32 v66, v66, v67
	s_waitcnt lgkmcnt(6)
	v_mfma_f32_32x32x16_bf16 v[114:129], v[162:165], v[130:133], v[50:65]
	ds_read_b128 v[86:89], v248 offset:36864
	ds_read_b128 v[216:219], v248 offset:41472
	v_exp_f32_e32 v70, v70
	v_exp_f32_e32 v71, v71
	v_add_f32_e32 v246, v68, v246
	v_add_f32_e32 v246, v69, v246
	v_cvt_pk_bf16_f32 v67, v68, v69
	v_mfma_f32_32x32x16_bf16 v[98:113], v[178:181], v[130:133], v[50:65]
	ds_read_b128 v[90:93], v248 offset:36896
	ds_read_b128 v[220:223], v248 offset:41504
	v_exp_f32_e32 v72, v72
	v_exp_f32_e32 v73, v73
	v_add_f32_e32 v246, v70, v246
	v_add_f32_e32 v246, v71, v246
	v_cvt_pk_bf16_f32 v68, v70, v71
	s_waitcnt lgkmcnt(8)
	v_mfma_f32_32x32x16_bf16 v[114:129], v[166:169], v[134:137], v[114:129]
	ds_read_b128 v[94:97], v248 offset:36928
	ds_read_b128 v[224:227], v248 offset:41536
	v_exp_f32_e32 v74, v74
	v_exp_f32_e32 v75, v75
	v_add_f32_e32 v246, v72, v246
	v_add_f32_e32 v246, v73, v246
	v_cvt_pk_bf16_f32 v69, v72, v73
	v_mfma_f32_32x32x16_bf16 v[98:113], v[182:185], v[134:137], v[98:113]
	ds_read_b128 v[212:215], v248 offset:36960
	ds_read_b128 v[242:245], v248 offset:41568
	v_exp_f32_e32 v76, v76
	v_exp_f32_e32 v77, v77
	v_add_f32_e32 v246, v74, v246
	v_add_f32_e32 v246, v75, v246
	v_cvt_pk_bf16_f32 v70, v74, v75
	s_waitcnt lgkmcnt(10)
	v_mfma_f32_32x32x16_bf16 v[114:129], v[170:173], v[138:141], v[114:129]
	v_exp_f32_e32 v78, v78
	v_exp_f32_e32 v79, v79
	v_add_f32_e32 v246, v76, v246
	v_add_f32_e32 v246, v77, v246
	v_cvt_pk_bf16_f32 v71, v76, v77
	v_mfma_f32_32x32x16_bf16 v[98:113], v[186:189], v[138:141], v[98:113]
	v_exp_f32_e32 v80, v80
	v_exp_f32_e32 v81, v81
	v_add_f32_e32 v246, v78, v246
	v_add_f32_e32 v246, v79, v246
	v_cvt_pk_bf16_f32 v72, v78, v79
	s_waitcnt lgkmcnt(8)
	v_mfma_f32_32x32x16_bf16 v[114:129], v[174:177], v[142:145], v[114:129]
	v_exp_f32_e32 v34, v34
	v_exp_f32_e32 v35, v35
	v_add_f32_e32 v246, v80, v246
	v_add_f32_e32 v246, v81, v246
	v_cvt_pk_bf16_f32 v73, v80, v81
	v_mfma_f32_32x32x16_bf16 v[98:113], v[82:85], v[142:145], v[98:113]
	v_exp_f32_e32 v36, v36
	v_exp_f32_e32 v37, v37
	v_add_f32_e32 v247, v34, v35
	v_cvt_pk_bf16_f32 v74, v34, v35
	s_waitcnt lgkmcnt(6)
	v_mfma_f32_32x32x16_bf16 v[18:33], v[86:89], v[66:69], v[18:33]
	v_exp_f32_e32 v38, v38
	v_exp_f32_e32 v39, v39
	v_add_f32_e32 v247, v36, v247
	v_add_f32_e32 v247, v37, v247
	v_cvt_pk_bf16_f32 v75, v36, v37
	v_mfma_f32_32x32x16_bf16 v[2:17], v[216:219], v[66:69], v[2:17]
	v_exp_f32_e32 v40, v40
	v_exp_f32_e32 v41, v41
	v_add_f32_e32 v247, v38, v247
	v_add_f32_e32 v247, v39, v247
	v_cvt_pk_bf16_f32 v76, v38, v39
	s_waitcnt lgkmcnt(4)
	v_mfma_f32_32x32x16_bf16 v[18:33], v[90:93], v[70:73], v[18:33]
	v_exp_f32_e32 v42, v42
	v_exp_f32_e32 v43, v43
	v_add_f32_e32 v247, v40, v247
	v_add_f32_e32 v247, v41, v247
	v_cvt_pk_bf16_f32 v77, v40, v41
	v_mfma_f32_32x32x16_bf16 v[2:17], v[220:223], v[70:73], v[2:17]
	v_exp_f32_e32 v44, v44
	v_exp_f32_e32 v45, v45
	v_add_f32_e32 v247, v42, v247
	v_add_f32_e32 v247, v43, v247
	v_cvt_pk_bf16_f32 v78, v42, v43
	s_waitcnt lgkmcnt(2)
	v_mfma_f32_32x32x16_bf16 v[18:33], v[94:97], v[74:77], v[18:33]
	v_exp_f32_e32 v46, v46
	v_exp_f32_e32 v47, v47
	v_add_f32_e32 v247, v44, v247
	v_add_f32_e32 v247, v45, v247
	v_cvt_pk_bf16_f32 v79, v44, v45
	v_mfma_f32_32x32x16_bf16 v[2:17], v[224:227], v[74:77], v[2:17]
	v_exp_f32_e32 v48, v48
	v_exp_f32_e32 v49, v49
	v_add_f32_e32 v247, v46, v247
	v_add_f32_e32 v247, v47, v247
	v_cvt_pk_bf16_f32 v80, v46, v47
	v_cvt_pk_bf16_f32 v81, v48, v49
	v_add_f32_e32 v247, v48, v247
	v_add_f32_e32 v247, v49, v247
	s_waitcnt lgkmcnt(0)
	v_mfma_f32_32x32x16_bf16 v[18:33], v[212:215], v[78:81], v[18:33]
	v_mfma_f32_32x32x16_bf16 v[2:17], v[242:245], v[78:81], v[2:17]
	v_add_f32_e32 v210, v210, v246
	v_add_f32_e32 v210, v210, v247
	s_cmp_ge_u32 s24, s16
	s_cbranch_scc1 .Lattn_fx_skipw1
	s_waitcnt vmcnt(2)
	ds_write_b128 v192, v[146:149] offset:18432
	ds_write_b128 v204, v[150:153] offset:27648
.Lattn_fx_skipw1:
	s_min_i32 s24, s10, s58
	s_mul_i32 s44, s24, 0xa0000
	s_add_u32 s44, s3, s44
	s_addc_u32 s45, s12, 0
	s_lshl_b32 s46, s24, 7
	s_add_u32 s46, s15, s46
	s_addc_u32 s47, s23, 0
	s_waitcnt lgkmcnt(0)
	s_barrier
	ds_read_b128 v[162:165], v193 offset:18432
	ds_read_b128 v[178:181], v193 offset:23040
	ds_read_b128 v[166:169], v193 offset:18464
	ds_read_b128 v[182:185], v193 offset:23072
	ds_read_b128 v[170:173], v193 offset:18496
	ds_read_b128 v[186:189], v193 offset:23104
	ds_read_b128 v[174:177], v193 offset:18528
	ds_read_b128 v[82:85], v193 offset:23136
	global_load_dwordx4 v[146:149], v252, s[44:45] offset:1024
	global_load_dwordx4 v[150:153], v253, s[46:47]
	v_exp_f32_e32 v114, v114
	v_exp_f32_e32 v115, v115
	v_exp_f32_e32 v116, v116
	v_exp_f32_e32 v117, v117
	v_add_f32_e32 v246, v114, v115
	v_cvt_pk_bf16_f32 v114, v114, v115
	s_waitcnt lgkmcnt(6)
	v_mfma_f32_32x32x16_bf16 v[66:81], v[162:165], v[130:133], v[50:65]
	ds_read_b128 v[86:89], v248
	ds_read_b128 v[216:219], v248 offset:4608
	v_exp_f32_e32 v118, v118
	v_exp_f32_e32 v119, v119
	v_add_f32_e32 v246, v116, v246
	v_add_f32_e32 v246, v117, v246
	v_cvt_pk_bf16_f32 v115, v116, v117
	v_mfma_f32_32x32x16_bf16 v[34:49], v[178:181], v[130:133], v[50:65]
	ds_read_b128 v[90:93], v248 offset:32
	ds_read_b128 v[220:223], v248 offset:4640
	v_exp_f32_e32 v120, v120
	v_exp_f32_e32 v121, v121
	v_add_f32_e32 v246, v118, v246
	v_add_f32_e32 v246, v119, v246
	v_cvt_pk_bf16_f32 v116, v118, v119
	s_waitcnt lgkmcnt(8)
	v_mfma_f32_32x32x16_bf16 v[66:81], v[166:169], v[134:137], v[66:81]
	ds_read_b128 v[94:97], v248 offset:64
	ds_read_b128 v[224:227], v248 offset:4672
	v_exp_f32_e32 v122, v122
	v_exp_f32_e32 v123, v123
	v_add_f32_e32 v246, v120, v246
	v_add_f32_e32 v246, v121, v246
	v_cvt_pk_bf16_f32 v117, v120, v121
	v_mfma_f32_32x32x16_bf16 v[34:49], v[182:185], v[134:137], v[34:49]
	ds_read_b128 v[212:215], v248 offset:96
	ds_read_b128 v[242:245], v248 offset:4704
	v_exp_f32_e32 v124, v124
	v_exp_f32_e32 v125, v125
	v_add_f32_e32 v246, v122, v246
	v_add_f32_e32 v246, v123, v246
	v_cvt_pk_bf16_f32 v118, v122, v123
	s_waitcnt lgkmcnt(10)
	v_mfma_f32_32x32x16_bf16 v[66:81], v[170:173], v[138:141], v[66:81]
	v_exp_f32_e32 v126, v126
	v_exp_f32_e32 v127, v127
	v_add_f32_e32 v246, v124, v246
	v_add_f32_e32 v246, v125, v246
	v_cvt_pk_bf16_f32 v119, v124, v125
	v_mfma_f32_32x32x16_bf16 v[34:49], v[186:189], v[138:141], v[34:49]
	v_exp_f32_e32 v128, v128
	v_exp_f32_e32 v129, v129
	v_add_f32_e32 v246, v126, v246
	v_add_f32_e32 v246, v127, v246
	v_cvt_pk_bf16_f32 v120, v126, v127
	s_waitcnt lgkmcnt(8)
	v_mfma_f32_32x32x16_bf16 v[66:81], v[174:177], v[142:145], v[66:81]
	v_exp_f32_e32 v98, v98
	v_exp_f32_e32 v99, v99
	v_add_f32_e32 v246, v128, v246
	v_add_f32_e32 v246, v129, v246
	v_cvt_pk_bf16_f32 v121, v128, v129
	v_mfma_f32_32x32x16_bf16 v[34:49], v[82:85], v[142:145], v[34:49]
	v_exp_f32_e32 v100, v100
	v_exp_f32_e32 v101, v101
	v_add_f32_e32 v247, v98, v99
	v_cvt_pk_bf16_f32 v122, v98, v99
	s_waitcnt lgkmcnt(6)
	v_mfma_f32_32x32x16_bf16 v[18:33], v[86:89], v[114:117], v[18:33]
	v_exp_f32_e32 v102, v102
	v_exp_f32_e32 v103, v103
	v_add_f32_e32 v247, v100, v247
	v_add_f32_e32 v247, v101, v247
	v_cvt_pk_bf16_f32 v123, v100, v101
	v_mfma_f32_32x32x16_bf16 v[2:17], v[216:219], v[114:117], v[2:17]
	v_exp_f32_e32 v104, v104
	v_exp_f32_e32 v105, v105
	v_add_f32_e32 v247, v102, v247
	v_add_f32_e32 v247, v103, v247
	v_cvt_pk_bf16_f32 v124, v102, v103
	s_waitcnt lgkmcnt(4)
	v_mfma_f32_32x32x16_bf16 v[18:33], v[90:93], v[118:121], v[18:33]
	v_exp_f32_e32 v106, v106
	v_exp_f32_e32 v107, v107
	v_add_f32_e32 v247, v104, v247
	v_add_f32_e32 v247, v105, v247
	v_cvt_pk_bf16_f32 v125, v104, v105
	v_mfma_f32_32x32x16_bf16 v[2:17], v[220:223], v[118:121], v[2:17]
	v_exp_f32_e32 v108, v108
	v_exp_f32_e32 v109, v109
	v_add_f32_e32 v247, v106, v247
	v_add_f32_e32 v247, v107, v247
	v_cvt_pk_bf16_f32 v126, v106, v107
	s_waitcnt lgkmcnt(2)
	v_mfma_f32_32x32x16_bf16 v[18:33], v[94:97], v[122:125], v[18:33]
	v_exp_f32_e32 v110, v110
	v_exp_f32_e32 v111, v111
	v_add_f32_e32 v247, v108, v247
	v_add_f32_e32 v247, v109, v247
	v_cvt_pk_bf16_f32 v127, v108, v109
	v_mfma_f32_32x32x16_bf16 v[2:17], v[224:227], v[122:125], v[2:17]
	v_exp_f32_e32 v112, v112
	v_exp_f32_e32 v113, v113
	v_add_f32_e32 v247, v110, v247
	v_add_f32_e32 v247, v111, v247
	v_cvt_pk_bf16_f32 v128, v110, v111
	v_cvt_pk_bf16_f32 v129, v112, v113
	v_add_f32_e32 v247, v112, v247
	v_add_f32_e32 v247, v113, v247
	s_waitcnt lgkmcnt(0)
	v_mfma_f32_32x32x16_bf16 v[18:33], v[212:215], v[126:129], v[18:33]
	v_mfma_f32_32x32x16_bf16 v[2:17], v[242:245], v[126:129], v[2:17]
	v_add_f32_e32 v210, v210, v246
	v_add_f32_e32 v210, v210, v247
	s_cmp_ge_u32 s11, s16
	s_cbranch_scc1 .Lattn_fx_skipw2
	s_waitcnt vmcnt(2)
	ds_write_b128 v192, v[154:157] offset:55296
	ds_write_b128 v204, v[158:161] offset:64512
.Lattn_fx_skipw2:
	s_add_i32 s10, s10, 2
	s_cmp_lt_u32 s11, s16
	s_cbranch_scc0 .Lattn_fx_exit0
	s_add_i32 s11, s10, -1
	s_min_i32 s1, s11, s58
	s_mul_i32 s44, s1, 0xa0000
	s_add_u32 s44, s3, s44
	s_addc_u32 s45, s12, 0
	s_lshl_b32 s46, s1, 7
	s_add_u32 s46, s15, s46
	s_addc_u32 s47, s23, 0
	s_add_i32 s24, s10, -2
	s_cmp_lt_u32 s24, s16
	s_cselect_b64 s[0:1], -1, 0
	s_waitcnt lgkmcnt(0)
	s_barrier
	ds_read_b128 v[162:165], v193 offset:55296
	ds_read_b128 v[178:181], v193 offset:59904
	ds_read_b128 v[166:169], v193 offset:55328
	ds_read_b128 v[182:185], v193 offset:59936
	ds_read_b128 v[170:173], v193 offset:55360
	ds_read_b128 v[186:189], v193 offset:59968
	ds_read_b128 v[174:177], v193 offset:55392
	ds_read_b128 v[82:85], v193 offset:60000
	global_load_dwordx4 v[154:157], v252, s[44:45] offset:1024
	global_load_dwordx4 v[158:161], v253, s[46:47]
	v_exp_f32_e32 v66, v66
	v_exp_f32_e32 v67, v67
	v_exp_f32_e32 v68, v68
	v_exp_f32_e32 v69, v69
	v_add_f32_e32 v246, v66, v67
	v_cvt_pk_bf16_f32 v66, v66, v67
	s_waitcnt lgkmcnt(6)
	v_mfma_f32_32x32x16_bf16 v[114:129], v[162:165], v[130:133], v[50:65]
	ds_read_b128 v[86:89], v248 offset:18432
	ds_read_b128 v[216:219], v248 offset:23040
	v_exp_f32_e32 v70, v70
	v_exp_f32_e32 v71, v71
	v_add_f32_e32 v246, v68, v246
	v_add_f32_e32 v246, v69, v246
	v_cvt_pk_bf16_f32 v67, v68, v69
	v_mfma_f32_32x32x16_bf16 v[98:113], v[178:181], v[130:133], v[50:65]
	ds_read_b128 v[90:93], v248 offset:18464
	ds_read_b128 v[220:223], v248 offset:23072
	v_exp_f32_e32 v72, v72
	v_exp_f32_e32 v73, v73
	v_add_f32_e32 v246, v70, v246
	v_add_f32_e32 v246, v71, v246
	v_cvt_pk_bf16_f32 v68, v70, v71
	s_waitcnt lgkmcnt(8)
	v_mfma_f32_32x32x16_bf16 v[114:129], v[166:169], v[134:137], v[114:129]
	ds_read_b128 v[94:97], v248 offset:18496
	ds_read_b128 v[224:227], v248 offset:23104
	v_exp_f32_e32 v74, v74
	v_exp_f32_e32 v75, v75
	v_add_f32_e32 v246, v72, v246
	v_add_f32_e32 v246, v73, v246
	v_cvt_pk_bf16_f32 v69, v72, v73
	v_mfma_f32_32x32x16_bf16 v[98:113], v[182:185], v[134:137], v[98:113]
	ds_read_b128 v[212:215], v248 offset:18528
	ds_read_b128 v[242:245], v248 offset:23136
	v_exp_f32_e32 v76, v76
	v_exp_f32_e32 v77, v77
	v_add_f32_e32 v246, v74, v246
	v_add_f32_e32 v246, v75, v246
	v_cvt_pk_bf16_f32 v70, v74, v75
	s_waitcnt lgkmcnt(10)
	v_mfma_f32_32x32x16_bf16 v[114:129], v[170:173], v[138:141], v[114:129]
	v_exp_f32_e32 v78, v78
	v_exp_f32_e32 v79, v79
	v_add_f32_e32 v246, v76, v246
	v_add_f32_e32 v246, v77, v246
	v_cvt_pk_bf16_f32 v71, v76, v77
	v_mfma_f32_32x32x16_bf16 v[98:113], v[186:189], v[138:141], v[98:113]
	v_exp_f32_e32 v80, v80
	v_exp_f32_e32 v81, v81
	v_add_f32_e32 v246, v78, v246
	v_add_f32_e32 v246, v79, v246
	v_cvt_pk_bf16_f32 v72, v78, v79
	s_waitcnt lgkmcnt(8)
	v_mfma_f32_32x32x16_bf16 v[114:129], v[174:177], v[142:145], v[114:129]
	v_exp_f32_e32 v34, v34
	v_exp_f32_e32 v35, v35
	v_add_f32_e32 v246, v80, v246
	v_add_f32_e32 v246, v81, v246
	v_cvt_pk_bf16_f32 v73, v80, v81
	v_mfma_f32_32x32x16_bf16 v[98:113], v[82:85], v[142:145], v[98:113]
	v_exp_f32_e32 v36, v36
	v_exp_f32_e32 v37, v37
	v_add_f32_e32 v247, v34, v35
	v_cvt_pk_bf16_f32 v74, v34, v35
	s_waitcnt lgkmcnt(6)
	v_mfma_f32_32x32x16_bf16 v[18:33], v[86:89], v[66:69], v[18:33]
	v_exp_f32_e32 v38, v38
	v_exp_f32_e32 v39, v39
	v_add_f32_e32 v247, v36, v247
	v_add_f32_e32 v247, v37, v247
	v_cvt_pk_bf16_f32 v75, v36, v37
	v_mfma_f32_32x32x16_bf16 v[2:17], v[216:219], v[66:69], v[2:17]
	v_exp_f32_e32 v40, v40
	v_exp_f32_e32 v41, v41
	v_add_f32_e32 v247, v38, v247
	v_add_f32_e32 v247, v39, v247
	v_cvt_pk_bf16_f32 v76, v38, v39
	s_waitcnt lgkmcnt(4)
	v_mfma_f32_32x32x16_bf16 v[18:33], v[90:93], v[70:73], v[18:33]
	v_exp_f32_e32 v42, v42
	v_exp_f32_e32 v43, v43
	v_add_f32_e32 v247, v40, v247
	v_add_f32_e32 v247, v41, v247
	v_cvt_pk_bf16_f32 v77, v40, v41
	v_mfma_f32_32x32x16_bf16 v[2:17], v[220:223], v[70:73], v[2:17]
	v_exp_f32_e32 v44, v44
	v_exp_f32_e32 v45, v45
	v_add_f32_e32 v247, v42, v247
	v_add_f32_e32 v247, v43, v247
	v_cvt_pk_bf16_f32 v78, v42, v43
	s_waitcnt lgkmcnt(2)
	v_mfma_f32_32x32x16_bf16 v[18:33], v[94:97], v[74:77], v[18:33]
	v_exp_f32_e32 v46, v46
	v_exp_f32_e32 v47, v47
	v_add_f32_e32 v247, v44, v247
	v_add_f32_e32 v247, v45, v247
	v_cvt_pk_bf16_f32 v79, v44, v45
	v_mfma_f32_32x32x16_bf16 v[2:17], v[224:227], v[74:77], v[2:17]
	v_exp_f32_e32 v48, v48
	v_exp_f32_e32 v49, v49
	v_add_f32_e32 v247, v46, v247
	v_add_f32_e32 v247, v47, v247
	v_cvt_pk_bf16_f32 v80, v46, v47
	v_cvt_pk_bf16_f32 v81, v48, v49
	v_add_f32_e32 v247, v48, v247
	v_add_f32_e32 v247, v49, v247
	s_waitcnt lgkmcnt(0)
	v_mfma_f32_32x32x16_bf16 v[18:33], v[212:215], v[78:81], v[18:33]
	v_mfma_f32_32x32x16_bf16 v[2:17], v[242:245], v[78:81], v[2:17]
	v_add_f32_e32 v210, v210, v246
	v_add_f32_e32 v210, v210, v247
	s_cmp_ge_u32 s24, s16
	s_cbranch_scc1 .Lattn_fx_skipw3
	s_waitcnt vmcnt(2)
	ds_write_b128 v192, v[146:149] offset:36864
	ds_write_b128 v204, v[150:153] offset:46080
.Lattn_fx_skipw3:
	s_min_i32 s24, s10, s58
	s_mul_i32 s44, s24, 0xa0000
	s_add_u32 s44, s3, s44
	s_addc_u32 s45, s12, 0
	s_lshl_b32 s46, s24, 7
	s_add_u32 s46, s15, s46
	s_addc_u32 s47, s23, 0
	s_waitcnt lgkmcnt(0)
	s_barrier
	ds_read_b128 v[162:165], v193 offset:36864
	ds_read_b128 v[178:181], v193 offset:41472
	ds_read_b128 v[166:169], v193 offset:36896
	ds_read_b128 v[182:185], v193 offset:41504
	ds_read_b128 v[170:173], v193 offset:36928
	ds_read_b128 v[186:189], v193 offset:41536
	ds_read_b128 v[174:177], v193 offset:36960
	ds_read_b128 v[82:85], v193 offset:41568
	global_load_dwordx4 v[146:149], v252, s[44:45] offset:1024
	global_load_dwordx4 v[150:153], v253, s[46:47]
	v_exp_f32_e32 v114, v114
	v_exp_f32_e32 v115, v115
	v_exp_f32_e32 v116, v116
	v_exp_f32_e32 v117, v117
	v_add_f32_e32 v246, v114, v115
	v_cvt_pk_bf16_f32 v114, v114, v115
	s_waitcnt lgkmcnt(6)
	v_mfma_f32_32x32x16_bf16 v[66:81], v[162:165], v[130:133], v[50:65]
	ds_read_b128 v[86:89], v248 offset:55296
	ds_read_b128 v[216:219], v248 offset:59904
	v_exp_f32_e32 v118, v118
	v_exp_f32_e32 v119, v119
	v_add_f32_e32 v246, v116, v246
	v_add_f32_e32 v246, v117, v246
	v_cvt_pk_bf16_f32 v115, v116, v117
	v_mfma_f32_32x32x16_bf16 v[34:49], v[178:181], v[130:133], v[50:65]
	ds_read_b128 v[90:93], v248 offset:55328
	ds_read_b128 v[220:223], v248 offset:59936
	v_exp_f32_e32 v120, v120
	v_exp_f32_e32 v121, v121
	v_add_f32_e32 v246, v118, v246
	v_add_f32_e32 v246, v119, v246
	v_cvt_pk_bf16_f32 v116, v118, v119
	s_waitcnt lgkmcnt(8)
	v_mfma_f32_32x32x16_bf16 v[66:81], v[166:169], v[134:137], v[66:81]
	ds_read_b128 v[94:97], v248 offset:55360
	ds_read_b128 v[224:227], v248 offset:59968
	v_exp_f32_e32 v122, v122
	v_exp_f32_e32 v123, v123
	v_add_f32_e32 v246, v120, v246
	v_add_f32_e32 v246, v121, v246
	v_cvt_pk_bf16_f32 v117, v120, v121
	v_mfma_f32_32x32x16_bf16 v[34:49], v[182:185], v[134:137], v[34:49]
	ds_read_b128 v[212:215], v248 offset:55392
	ds_read_b128 v[242:245], v248 offset:60000
	v_exp_f32_e32 v124, v124
	v_exp_f32_e32 v125, v125
	v_add_f32_e32 v246, v122, v246
	v_add_f32_e32 v246, v123, v246
	v_cvt_pk_bf16_f32 v118, v122, v123
	s_waitcnt lgkmcnt(10)
	v_mfma_f32_32x32x16_bf16 v[66:81], v[170:173], v[138:141], v[66:81]
	v_exp_f32_e32 v126, v126
	v_exp_f32_e32 v127, v127
	v_add_f32_e32 v246, v124, v246
	v_add_f32_e32 v246, v125, v246
	v_cvt_pk_bf16_f32 v119, v124, v125
	v_mfma_f32_32x32x16_bf16 v[34:49], v[186:189], v[138:141], v[34:49]
	v_exp_f32_e32 v128, v128
	v_exp_f32_e32 v129, v129
	v_add_f32_e32 v246, v126, v246
	v_add_f32_e32 v246, v127, v246
	v_cvt_pk_bf16_f32 v120, v126, v127
	s_waitcnt lgkmcnt(8)
	v_mfma_f32_32x32x16_bf16 v[66:81], v[174:177], v[142:145], v[66:81]
	v_exp_f32_e32 v98, v98
	v_exp_f32_e32 v99, v99
	v_add_f32_e32 v246, v128, v246
	v_add_f32_e32 v246, v129, v246
	v_cvt_pk_bf16_f32 v121, v128, v129
	v_mfma_f32_32x32x16_bf16 v[34:49], v[82:85], v[142:145], v[34:49]
	v_exp_f32_e32 v100, v100
	v_exp_f32_e32 v101, v101
	v_add_f32_e32 v247, v98, v99
	v_cvt_pk_bf16_f32 v122, v98, v99
	s_waitcnt lgkmcnt(6)
	v_mfma_f32_32x32x16_bf16 v[18:33], v[86:89], v[114:117], v[18:33]
	v_exp_f32_e32 v102, v102
	v_exp_f32_e32 v103, v103
	v_add_f32_e32 v247, v100, v247
	v_add_f32_e32 v247, v101, v247
	v_cvt_pk_bf16_f32 v123, v100, v101
	v_mfma_f32_32x32x16_bf16 v[2:17], v[216:219], v[114:117], v[2:17]
	v_exp_f32_e32 v104, v104
	v_exp_f32_e32 v105, v105
	v_add_f32_e32 v247, v102, v247
	v_add_f32_e32 v247, v103, v247
	v_cvt_pk_bf16_f32 v124, v102, v103
	s_waitcnt lgkmcnt(4)
	v_mfma_f32_32x32x16_bf16 v[18:33], v[90:93], v[118:121], v[18:33]
	v_exp_f32_e32 v106, v106
	v_exp_f32_e32 v107, v107
	v_add_f32_e32 v247, v104, v247
	v_add_f32_e32 v247, v105, v247
	v_cvt_pk_bf16_f32 v125, v104, v105
	v_mfma_f32_32x32x16_bf16 v[2:17], v[220:223], v[118:121], v[2:17]
	v_exp_f32_e32 v108, v108
	v_exp_f32_e32 v109, v109
	v_add_f32_e32 v247, v106, v247
	v_add_f32_e32 v247, v107, v247
	v_cvt_pk_bf16_f32 v126, v106, v107
	s_waitcnt lgkmcnt(2)
	v_mfma_f32_32x32x16_bf16 v[18:33], v[94:97], v[122:125], v[18:33]
	v_exp_f32_e32 v110, v110
	v_exp_f32_e32 v111, v111
	v_add_f32_e32 v247, v108, v247
	v_add_f32_e32 v247, v109, v247
	v_cvt_pk_bf16_f32 v127, v108, v109
	v_mfma_f32_32x32x16_bf16 v[2:17], v[224:227], v[122:125], v[2:17]
	v_exp_f32_e32 v112, v112
	v_exp_f32_e32 v113, v113
	v_add_f32_e32 v247, v110, v247
	v_add_f32_e32 v247, v111, v247
	v_cvt_pk_bf16_f32 v128, v110, v111
	v_cvt_pk_bf16_f32 v129, v112, v113
	v_add_f32_e32 v247, v112, v247
	v_add_f32_e32 v247, v113, v247
	s_waitcnt lgkmcnt(0)
	v_mfma_f32_32x32x16_bf16 v[18:33], v[212:215], v[126:129], v[18:33]
	v_mfma_f32_32x32x16_bf16 v[2:17], v[242:245], v[126:129], v[2:17]
	v_add_f32_e32 v210, v210, v246
	v_add_f32_e32 v210, v210, v247
	s_cmp_ge_u32 s11, s16
	s_cbranch_scc1 .Lattn_fx_skipw4
	s_waitcnt vmcnt(2)
	ds_write_b128 v192, v[154:157]
	ds_write_b128 v204, v[158:161] offset:9216
